# q-GEMM rope epilogue: cos/sin rows loaded once per tile up front instead of a serialized load+wait per step (on top of fast MLA loop)
# speedup vs baseline: 1.0139x; 1.0018x over previous
; #define GAS __attribute__((address_space(1)))
;     __device__ __forceinline__ void operator()(const f32x4 (&acc)[2][2][4][2], const Unit& u, int wr, int wc, int fr, int fq) const {
;     ...
;                 const int row = u.pm * 256 + ai * 128 + wr * 64 + m * 16 + fr;
; #pragma unroll
;                 for (int bj = 0; bj < 2; ++bj) {
;                     const int c0 = u.pn * 256 + bj * 128 + wc * 32;
;                     f32x4 a = acc[ai][bj][m][0] * sc, b = acc[ai][bj][m][1] * sc;
;                     if ((c0 % 96) == 64) {
;                         const f32x4 cs = *(const GAS f32x4*)(cosT + (size_t)row * 16 + 4 * fq), sn = *(const GAS f32x4*)(sinT + (size_t)row * 16 + 4 * fq);
;                         const f32x4 ra = a * cs - b * sn, rb = b * cs + a * sn; a = ra; b = rb;
;                     }
;                     u32x2 w0, w1; w0.x = pk2(a[0], a[1]); w0.y = pk2(a[2], a[3]); w1.x = pk2(b[0], b[1]); w1.y = pk2(b[2], b[3]);
;                     GAS bf16_t* qp = Q + (size_t)row * 768 + c0 + 4 * fq;
;                     *(GAS u32x2*)qp = w0; *(GAS u32x2*)(qp + 16) = w1;
;                 }
.LBB0_719:
	v_lshl_add_u32 v14, s8, 8, v156
	v_lshlrev_b32_e32 v246, 6, v14
	v_mov_b32_e32 v247, 0
	v_lshl_add_u64 v[242:243], v[146:147], 0, v[246:247]
	v_lshl_add_u64 v[244:245], v[144:145], 0, v[246:247]
	global_load_dwordx4 v[172:175], v[242:243], off
	global_load_dwordx4 v[176:179], v[244:245], off
	global_load_dwordx4 v[188:191], v[242:243], off offset:1024
	global_load_dwordx4 v[192:195], v[244:245], off offset:1024
	global_load_dwordx4 v[196:199], v[242:243], off offset:2048
	global_load_dwordx4 v[200:203], v[244:245], off offset:2048
	global_load_dwordx4 v[204:207], v[242:243], off offset:3072
	global_load_dwordx4 v[208:211], v[244:245], off offset:3072
	v_mov_b32_e32 v246, 0x2000
	v_lshl_add_u64 v[242:243], v[242:243], 0, v[246:247]
	v_lshl_add_u64 v[244:245], v[244:245], 0, v[246:247]
	global_load_dwordx4 v[212:215], v[242:243], off
	global_load_dwordx4 v[216:219], v[244:245], off
	global_load_dwordx4 v[220:223], v[242:243], off offset:1024
	global_load_dwordx4 v[224:227], v[244:245], off offset:1024
	global_load_dwordx4 v[228:231], v[242:243], off offset:2048
	global_load_dwordx4 v[232:235], v[244:245], off offset:2048
	global_load_dwordx4 v[180:183], v[242:243], off offset:3072
	global_load_dwordx4 v[236:239], v[244:245], off offset:3072
	s_waitcnt vmcnt(0)
	s_lshl_b32 s8, s78, 8
	s_or_b32 s58, s8, s17
	s_mul_hi_i32 s8, s58, 0x2aaaaaab
	s_lshr_b32 s9, s8, 31
	s_lshr_b32 s8, s8, 4
	s_add_i32 s8, s8, s9
	v_ashrrev_i32_e32 v15, 31, v14
	s_mulk_i32 s8, 0x60
	v_lshlrev_b64 v[16:17], 4, v[14:15]
	s_sub_i32 s8, s58, s8
	s_cmp_eq_u32 s8, 64
	v_lshlrev_b64 v[22:23], 2, v[16:17]
	s_cselect_b64 s[10:11], -1, 0
	s_cmp_lg_u32 s8, 64
	v_lshl_add_u64 v[16:17], v[144:145], 0, v[22:23]
	v_lshl_add_u64 v[22:23], v[146:147], 0, v[22:23]
	s_cbranch_scc1 .LBB0_721
	v_mov_b32_e32 v162, v172
	v_mov_b32_e32 v163, v173
	v_mov_b32_e32 v164, v174
	v_mov_b32_e32 v165, v175
	v_mov_b32_e32 v166, v176
	v_mov_b32_e32 v167, v177
	v_mov_b32_e32 v168, v178
	v_mov_b32_e32 v169, v179
	v_pk_mul_f32 v[24:25], v[132:133], v[164:165]
	v_pk_mul_f32 v[170:171], v[130:131], v[162:163]
	v_pk_mul_f32 v[164:165], v[136:137], v[164:165]
	v_pk_mul_f32 v[162:163], v[134:135], v[162:163]
	v_pk_fma_f32 v[136:137], v[136:137], v[168:169], v[24:25] neg_lo:[0,0,1] neg_hi:[0,0,1]
	v_pk_fma_f32 v[134:135], v[134:135], v[166:167], v[170:171] neg_lo:[0,0,1] neg_hi:[0,0,1]
	v_pk_fma_f32 v[132:133], v[132:133], v[168:169], v[164:165]
	v_pk_fma_f32 v[130:131], v[130:131], v[166:167], v[162:163]
.LBB0_721:
	v_mov_b64_e32 v[24:25], s[36:37]
	v_mad_i64_i32 v[24:25], s[8:9], v14, s77, v[24:25]
	s_or_b32 s8, s58, 0x80
	s_mul_hi_i32 s9, s8, 0x2aaaaaab
	s_lshr_b32 s21, s9, 31
	s_lshr_b32 s9, s9, 4
	s_add_i32 s9, s9, s21
	s_mulk_i32 s9, 0x60
	s_ashr_i32 s59, s58, 31
	s_sub_i32 s8, s8, s9
	v_lshl_add_u64 v[24:25], s[58:59], 1, v[24:25]
	s_cmp_eq_u32 s8, 64
	v_cvt_pk_bf16_f32 v134, v134, v135
	v_cvt_pk_bf16_f32 v135, v136, v137
	v_cvt_pk_bf16_f32 v130, v130, v131
	v_cvt_pk_bf16_f32 v131, v132, v133
	v_lshl_add_u64 v[24:25], v[142:143], 1, v[24:25]
	s_cselect_b64 s[60:61], -1, 0
	s_cmp_lg_u32 s8, 64
	global_store_dwordx2 v[24:25], v[134:135], off
	global_store_dwordx2 v[24:25], v[130:131], off offset:32
	s_cbranch_scc1 .LBB0_723
	v_mov_b32_e32 v130, v172
	v_mov_b32_e32 v131, v173
	v_mov_b32_e32 v132, v174
	v_mov_b32_e32 v133, v175
	v_mov_b32_e32 v134, v176
	v_mov_b32_e32 v135, v177
	v_mov_b32_e32 v136, v178
	v_mov_b32_e32 v137, v179
	v_pk_mul_f32 v[16:17], v[124:125], v[132:133]
	v_pk_mul_f32 v[22:23], v[122:123], v[130:131]
	v_pk_mul_f32 v[132:133], v[128:129], v[132:133]
	v_pk_mul_f32 v[130:131], v[126:127], v[130:131]
	v_pk_fma_f32 v[128:129], v[128:129], v[136:137], v[16:17] neg_lo:[0,0,1] neg_hi:[0,0,1]
	v_pk_fma_f32 v[126:127], v[126:127], v[134:135], v[22:23] neg_lo:[0,0,1] neg_hi:[0,0,1]
	v_pk_fma_f32 v[124:125], v[124:125], v[136:137], v[132:133]
	v_pk_fma_f32 v[122:123], v[122:123], v[134:135], v[130:131]
.LBB0_723:
	v_cvt_pk_bf16_f32 v16, v126, v127
	v_cvt_pk_bf16_f32 v17, v128, v129
	v_cvt_pk_bf16_f32 v22, v122, v123
	v_cvt_pk_bf16_f32 v23, v124, v125
	global_store_dwordx2 v[24:25], v[16:17], off offset:256
	global_store_dwordx2 v[24:25], v[22:23], off offset:288
	v_or_b32_e32 v24, 16, v14
	v_ashrrev_i32_e32 v25, 31, v24
	v_lshlrev_b64 v[16:17], 4, v[24:25]
	v_cndmask_b32_e64 v1, 0, 1, s[10:11]
	v_lshlrev_b64 v[22:23], 2, v[16:17]
	v_cmp_ne_u32_e64 s[8:9], 1, v1
	s_andn2_b64 vcc, exec, s[10:11]
	v_lshl_add_u64 v[16:17], v[144:145], 0, v[22:23]
	v_lshl_add_u64 v[22:23], v[146:147], 0, v[22:23]
	s_cbranch_vccnz .LBB0_725
	v_mov_b32_e32 v122, v188
	v_mov_b32_e32 v123, v189
	v_mov_b32_e32 v124, v190
	v_mov_b32_e32 v125, v191
	v_mov_b32_e32 v126, v192
	v_mov_b32_e32 v127, v193
	v_mov_b32_e32 v128, v194
	v_mov_b32_e32 v129, v195
	v_pk_mul_f32 v[130:131], v[116:117], v[124:125]
	v_pk_mul_f32 v[132:133], v[114:115], v[122:123]
	v_pk_mul_f32 v[124:125], v[120:121], v[124:125]
	v_pk_mul_f32 v[122:123], v[118:119], v[122:123]
	v_pk_fma_f32 v[120:121], v[120:121], v[128:129], v[130:131] neg_lo:[0,0,1] neg_hi:[0,0,1]
	v_pk_fma_f32 v[118:119], v[118:119], v[126:127], v[132:133] neg_lo:[0,0,1] neg_hi:[0,0,1]
	v_pk_fma_f32 v[116:117], v[116:117], v[128:129], v[124:125]
	v_pk_fma_f32 v[114:115], v[114:115], v[126:127], v[122:123]
; #define GAS __attribute__((address_space(1)))
;     __device__ __forceinline__ void operator()(const f32x4 (&acc)[2][2][4][2], const Unit& u, int wr, int wc, int fr, int fq) const {
;     ...
;                 const int row = u.pm * 256 + ai * 128 + wr * 64 + m * 16 + fr;
; #pragma unroll
;                 for (int bj = 0; bj < 2; ++bj) {
;                     const int c0 = u.pn * 256 + bj * 128 + wc * 32;
;                     f32x4 a = acc[ai][bj][m][0] * sc, b = acc[ai][bj][m][1] * sc;
;                     if ((c0 % 96) == 64) {
;                         const f32x4 cs = *(const GAS f32x4*)(cosT + (size_t)row * 16 + 4 * fq), sn = *(const GAS f32x4*)(sinT + (size_t)row * 16 + 4 * fq);
;                         const f32x4 ra = a * cs - b * sn, rb = b * cs + a * sn; a = ra; b = rb;
;                     }
;                     u32x2 w0, w1; w0.x = pk2(a[0], a[1]); w0.y = pk2(a[2], a[3]); w1.x = pk2(b[0], b[1]); w1.y = pk2(b[2], b[3]);
;                     GAS bf16_t* qp = Q + (size_t)row * 768 + c0 + 4 * fq;
;                     *(GAS u32x2*)qp = w0; *(GAS u32x2*)(qp + 16) = w1;
;                 }
.LBB0_725:
	s_nop 0
	v_cvt_pk_bf16_f32 v114, v114, v115
	v_cvt_pk_bf16_f32 v115, v116, v117
	v_mov_b64_e32 v[116:117], s[36:37]
	v_mad_i64_i32 v[24:25], s[10:11], v24, s77, v[116:117]
	v_lshl_add_u64 v[24:25], s[58:59], 1, v[24:25]
	v_cndmask_b32_e64 v1, 0, 1, s[60:61]
	v_cvt_pk_bf16_f32 v118, v118, v119
	v_cvt_pk_bf16_f32 v119, v120, v121
	v_lshl_add_u64 v[24:25], v[142:143], 1, v[24:25]
	v_cmp_ne_u32_e64 s[10:11], 1, v1
	s_andn2_b64 vcc, exec, s[60:61]
	global_store_dwordx2 v[24:25], v[118:119], off
	global_store_dwordx2 v[24:25], v[114:115], off offset:32
	s_cbranch_vccnz .LBB0_727
	v_mov_b32_e32 v114, v188
	v_mov_b32_e32 v115, v189
	v_mov_b32_e32 v116, v190
	v_mov_b32_e32 v117, v191
	v_mov_b32_e32 v118, v192
	v_mov_b32_e32 v119, v193
	v_mov_b32_e32 v120, v194
	v_mov_b32_e32 v121, v195
	v_pk_mul_f32 v[16:17], v[108:109], v[116:117]
	v_pk_mul_f32 v[22:23], v[106:107], v[114:115]
	v_pk_mul_f32 v[116:117], v[112:113], v[116:117]
	v_pk_mul_f32 v[114:115], v[110:111], v[114:115]
	v_pk_fma_f32 v[112:113], v[112:113], v[120:121], v[16:17] neg_lo:[0,0,1] neg_hi:[0,0,1]
	v_pk_fma_f32 v[110:111], v[110:111], v[118:119], v[22:23] neg_lo:[0,0,1] neg_hi:[0,0,1]
	v_pk_fma_f32 v[108:109], v[108:109], v[120:121], v[116:117]
	v_pk_fma_f32 v[106:107], v[106:107], v[118:119], v[114:115]
.LBB0_727:
	v_cvt_pk_bf16_f32 v16, v110, v111
	v_cvt_pk_bf16_f32 v17, v112, v113
	v_cvt_pk_bf16_f32 v22, v106, v107
	v_cvt_pk_bf16_f32 v23, v108, v109
	global_store_dwordx2 v[24:25], v[16:17], off offset:256
	global_store_dwordx2 v[24:25], v[22:23], off offset:288
	v_or_b32_e32 v24, 32, v14
	v_ashrrev_i32_e32 v25, 31, v24
	v_lshlrev_b64 v[16:17], 4, v[24:25]
	v_lshlrev_b64 v[22:23], 2, v[16:17]
	s_and_b64 vcc, exec, s[8:9]
	v_lshl_add_u64 v[16:17], v[144:145], 0, v[22:23]
	v_lshl_add_u64 v[22:23], v[146:147], 0, v[22:23]
	s_cbranch_vccnz .LBB0_729
	v_mov_b32_e32 v106, v196
	v_mov_b32_e32 v107, v197
	v_mov_b32_e32 v108, v198
	v_mov_b32_e32 v109, v199
	v_mov_b32_e32 v110, v200
	v_mov_b32_e32 v111, v201
	v_mov_b32_e32 v112, v202
	v_mov_b32_e32 v113, v203
	v_pk_mul_f32 v[114:115], v[100:101], v[108:109]
	v_pk_mul_f32 v[116:117], v[98:99], v[106:107]
	v_pk_mul_f32 v[108:109], v[104:105], v[108:109]
	v_pk_mul_f32 v[106:107], v[102:103], v[106:107]
	v_pk_fma_f32 v[104:105], v[104:105], v[112:113], v[114:115] neg_lo:[0,0,1] neg_hi:[0,0,1]
	v_pk_fma_f32 v[102:103], v[102:103], v[110:111], v[116:117] neg_lo:[0,0,1] neg_hi:[0,0,1]
	v_pk_fma_f32 v[100:101], v[100:101], v[112:113], v[108:109]
	v_pk_fma_f32 v[98:99], v[98:99], v[110:111], v[106:107]
.LBB0_729:
	s_nop 0
	v_cvt_pk_bf16_f32 v98, v98, v99
	v_cvt_pk_bf16_f32 v99, v100, v101
	v_mov_b64_e32 v[100:101], s[36:37]
	v_mad_i64_i32 v[24:25], s[60:61], v24, s77, v[100:101]
	v_lshl_add_u64 v[24:25], s[58:59], 1, v[24:25]
	v_cvt_pk_bf16_f32 v102, v102, v103
	v_cvt_pk_bf16_f32 v103, v104, v105
	v_lshl_add_u64 v[24:25], v[142:143], 1, v[24:25]
	s_and_b64 vcc, exec, s[10:11]
	global_store_dwordx2 v[24:25], v[102:103], off
	global_store_dwordx2 v[24:25], v[98:99], off offset:32
	s_cbranch_vccnz .LBB0_731
	v_mov_b32_e32 v98, v196
	v_mov_b32_e32 v99, v197
	v_mov_b32_e32 v100, v198
	v_mov_b32_e32 v101, v199
	v_mov_b32_e32 v102, v200
	v_mov_b32_e32 v103, v201
	v_mov_b32_e32 v104, v202
	v_mov_b32_e32 v105, v203
	v_pk_mul_f32 v[16:17], v[92:93], v[100:101]
	v_pk_mul_f32 v[22:23], v[90:91], v[98:99]
	v_pk_mul_f32 v[100:101], v[96:97], v[100:101]
	v_pk_mul_f32 v[98:99], v[94:95], v[98:99]
	v_pk_fma_f32 v[96:97], v[96:97], v[104:105], v[16:17] neg_lo:[0,0,1] neg_hi:[0,0,1]
	v_pk_fma_f32 v[94:95], v[94:95], v[102:103], v[22:23] neg_lo:[0,0,1] neg_hi:[0,0,1]
	v_pk_fma_f32 v[92:93], v[92:93], v[104:105], v[100:101]
	v_pk_fma_f32 v[90:91], v[90:91], v[102:103], v[98:99]
.LBB0_731:
	v_cvt_pk_bf16_f32 v16, v94, v95
	v_cvt_pk_bf16_f32 v17, v96, v97
	v_cvt_pk_bf16_f32 v22, v90, v91
	v_cvt_pk_bf16_f32 v23, v92, v93
	global_store_dwordx2 v[24:25], v[16:17], off offset:256
	global_store_dwordx2 v[24:25], v[22:23], off offset:288
	v_or_b32_e32 v24, 48, v14
	v_ashrrev_i32_e32 v25, 31, v24
	v_lshlrev_b64 v[16:17], 4, v[24:25]
	v_lshlrev_b64 v[22:23], 2, v[16:17]
	s_and_b64 vcc, exec, s[8:9]
	v_lshl_add_u64 v[16:17], v[144:145], 0, v[22:23]
	v_lshl_add_u64 v[22:23], v[146:147], 0, v[22:23]
	s_cbranch_vccnz .LBB0_733
	v_mov_b32_e32 v90, v204
	v_mov_b32_e32 v91, v205
	v_mov_b32_e32 v92, v206
	v_mov_b32_e32 v93, v207
	v_mov_b32_e32 v94, v208
	v_mov_b32_e32 v95, v209
	v_mov_b32_e32 v96, v210
	v_mov_b32_e32 v97, v211
	v_pk_mul_f32 v[98:99], v[84:85], v[92:93]
	v_pk_mul_f32 v[100:101], v[82:83], v[90:91]
	v_pk_mul_f32 v[92:93], v[88:89], v[92:93]
	v_pk_mul_f32 v[90:91], v[86:87], v[90:91]
	v_pk_fma_f32 v[88:89], v[88:89], v[96:97], v[98:99] neg_lo:[0,0,1] neg_hi:[0,0,1]
	v_pk_fma_f32 v[86:87], v[86:87], v[94:95], v[100:101] neg_lo:[0,0,1] neg_hi:[0,0,1]
	v_pk_fma_f32 v[84:85], v[84:85], v[96:97], v[92:93]
	v_pk_fma_f32 v[82:83], v[82:83], v[94:95], v[90:91]
.LBB0_733:
	s_nop 0
	v_cvt_pk_bf16_f32 v82, v82, v83
	v_cvt_pk_bf16_f32 v83, v84, v85
	v_mov_b64_e32 v[84:85], s[36:37]
	v_mad_i64_i32 v[24:25], s[60:61], v24, s77, v[84:85]
	v_lshl_add_u64 v[24:25], s[58:59], 1, v[24:25]
	v_cvt_pk_bf16_f32 v86, v86, v87
	v_cvt_pk_bf16_f32 v87, v88, v89
	v_lshl_add_u64 v[24:25], v[142:143], 1, v[24:25]
	s_and_b64 vcc, exec, s[10:11]
	global_store_dwordx2 v[24:25], v[86:87], off
	global_store_dwordx2 v[24:25], v[82:83], off offset:32
	s_cbranch_vccnz .LBB0_735
	v_mov_b32_e32 v82, v204
	v_mov_b32_e32 v83, v205
	v_mov_b32_e32 v84, v206
	v_mov_b32_e32 v85, v207
	v_mov_b32_e32 v86, v208
	v_mov_b32_e32 v87, v209
	v_mov_b32_e32 v88, v210
	v_mov_b32_e32 v89, v211
	v_pk_mul_f32 v[16:17], v[76:77], v[84:85]
	v_pk_mul_f32 v[22:23], v[74:75], v[82:83]
	v_pk_mul_f32 v[84:85], v[80:81], v[84:85]
	v_pk_mul_f32 v[82:83], v[78:79], v[82:83]
	v_pk_fma_f32 v[80:81], v[80:81], v[88:89], v[16:17] neg_lo:[0,0,1] neg_hi:[0,0,1]
	v_pk_fma_f32 v[78:79], v[78:79], v[86:87], v[22:23] neg_lo:[0,0,1] neg_hi:[0,0,1]
	v_pk_fma_f32 v[76:77], v[76:77], v[88:89], v[84:85]
	v_pk_fma_f32 v[74:75], v[74:75], v[86:87], v[82:83]
; #define GAS __attribute__((address_space(1)))
;     __device__ __forceinline__ void operator()(const f32x4 (&acc)[2][2][4][2], const Unit& u, int wr, int wc, int fr, int fq) const {
;     ...
;                 const int row = u.pm * 256 + ai * 128 + wr * 64 + m * 16 + fr;
; #pragma unroll
;                 for (int bj = 0; bj < 2; ++bj) {
;                     const int c0 = u.pn * 256 + bj * 128 + wc * 32;
;                     f32x4 a = acc[ai][bj][m][0] * sc, b = acc[ai][bj][m][1] * sc;
;                     if ((c0 % 96) == 64) {
;                         const f32x4 cs = *(const GAS f32x4*)(cosT + (size_t)row * 16 + 4 * fq), sn = *(const GAS f32x4*)(sinT + (size_t)row * 16 + 4 * fq);
;                         const f32x4 ra = a * cs - b * sn, rb = b * cs + a * sn; a = ra; b = rb;
;                     }
;                     u32x2 w0, w1; w0.x = pk2(a[0], a[1]); w0.y = pk2(a[2], a[3]); w1.x = pk2(b[0], b[1]); w1.y = pk2(b[2], b[3]);
;                     GAS bf16_t* qp = Q + (size_t)row * 768 + c0 + 4 * fq;
;                     *(GAS u32x2*)qp = w0; *(GAS u32x2*)(qp + 16) = w1;
;                 }
.LBB0_735:
	v_cvt_pk_bf16_f32 v16, v78, v79
	v_cvt_pk_bf16_f32 v17, v80, v81
	v_cvt_pk_bf16_f32 v22, v74, v75
	v_cvt_pk_bf16_f32 v23, v76, v77
	global_store_dwordx2 v[24:25], v[16:17], off offset:256
	global_store_dwordx2 v[24:25], v[22:23], off offset:288
	v_add_u32_e32 v24, 0x80, v14
	v_ashrrev_i32_e32 v25, 31, v24
	v_lshlrev_b64 v[16:17], 4, v[24:25]
	v_lshlrev_b64 v[22:23], 2, v[16:17]
	s_and_b64 vcc, exec, s[8:9]
	v_lshl_add_u64 v[16:17], v[144:145], 0, v[22:23]
	v_lshl_add_u64 v[22:23], v[146:147], 0, v[22:23]
	s_cbranch_vccnz .LBB0_737
	v_mov_b32_e32 v74, v212
	v_mov_b32_e32 v75, v213
	v_mov_b32_e32 v76, v214
	v_mov_b32_e32 v77, v215
	v_mov_b32_e32 v78, v216
	v_mov_b32_e32 v79, v217
	v_mov_b32_e32 v80, v218
	v_mov_b32_e32 v81, v219
	v_pk_mul_f32 v[82:83], v[68:69], v[76:77]
	v_pk_mul_f32 v[84:85], v[66:67], v[74:75]
	v_pk_mul_f32 v[76:77], v[72:73], v[76:77]
	v_pk_mul_f32 v[74:75], v[70:71], v[74:75]
	v_pk_fma_f32 v[72:73], v[72:73], v[80:81], v[82:83] neg_lo:[0,0,1] neg_hi:[0,0,1]
	v_pk_fma_f32 v[70:71], v[70:71], v[78:79], v[84:85] neg_lo:[0,0,1] neg_hi:[0,0,1]
	v_pk_fma_f32 v[68:69], v[68:69], v[80:81], v[76:77]
	v_pk_fma_f32 v[66:67], v[66:67], v[78:79], v[74:75]
.LBB0_737:
	s_nop 0
	v_cvt_pk_bf16_f32 v66, v66, v67
	v_cvt_pk_bf16_f32 v67, v68, v69
	v_mov_b64_e32 v[68:69], s[36:37]
	v_mad_i64_i32 v[24:25], s[60:61], v24, s77, v[68:69]
	v_lshl_add_u64 v[24:25], s[58:59], 1, v[24:25]
	v_cvt_pk_bf16_f32 v70, v70, v71
	v_cvt_pk_bf16_f32 v71, v72, v73
	v_lshl_add_u64 v[24:25], v[142:143], 1, v[24:25]
	s_and_b64 vcc, exec, s[10:11]
	global_store_dwordx2 v[24:25], v[70:71], off
	global_store_dwordx2 v[24:25], v[66:67], off offset:32
	s_cbranch_vccnz .LBB0_739
	v_mov_b32_e32 v66, v212
	v_mov_b32_e32 v67, v213
	v_mov_b32_e32 v68, v214
	v_mov_b32_e32 v69, v215
	v_mov_b32_e32 v70, v216
	v_mov_b32_e32 v71, v217
	v_mov_b32_e32 v72, v218
	v_mov_b32_e32 v73, v219
	v_pk_mul_f32 v[16:17], v[60:61], v[68:69]
	v_pk_mul_f32 v[22:23], v[58:59], v[66:67]
	v_pk_mul_f32 v[68:69], v[64:65], v[68:69]
	v_pk_mul_f32 v[66:67], v[62:63], v[66:67]
	v_pk_fma_f32 v[64:65], v[64:65], v[72:73], v[16:17] neg_lo:[0,0,1] neg_hi:[0,0,1]
	v_pk_fma_f32 v[62:63], v[62:63], v[70:71], v[22:23] neg_lo:[0,0,1] neg_hi:[0,0,1]
	v_pk_fma_f32 v[60:61], v[60:61], v[72:73], v[68:69]
	v_pk_fma_f32 v[58:59], v[58:59], v[70:71], v[66:67]
.LBB0_739:
	v_cvt_pk_bf16_f32 v16, v62, v63
	v_cvt_pk_bf16_f32 v17, v64, v65
	v_cvt_pk_bf16_f32 v22, v58, v59
	v_cvt_pk_bf16_f32 v23, v60, v61
	global_store_dwordx2 v[24:25], v[16:17], off offset:256
	global_store_dwordx2 v[24:25], v[22:23], off offset:288
	v_add_u32_e32 v24, 0x90, v14
	v_ashrrev_i32_e32 v25, 31, v24
	v_lshlrev_b64 v[16:17], 4, v[24:25]
	v_lshlrev_b64 v[22:23], 2, v[16:17]
	s_and_b64 vcc, exec, s[8:9]
	v_lshl_add_u64 v[16:17], v[144:145], 0, v[22:23]
	v_lshl_add_u64 v[22:23], v[146:147], 0, v[22:23]
	s_cbranch_vccnz .LBB0_741
	v_mov_b32_e32 v58, v220
	v_mov_b32_e32 v59, v221
	v_mov_b32_e32 v60, v222
	v_mov_b32_e32 v61, v223
	v_mov_b32_e32 v62, v224
	v_mov_b32_e32 v63, v225
	v_mov_b32_e32 v64, v226
	v_mov_b32_e32 v65, v227
	v_pk_mul_f32 v[66:67], v[52:53], v[60:61]
	v_pk_mul_f32 v[68:69], v[50:51], v[58:59]
	v_pk_mul_f32 v[60:61], v[56:57], v[60:61]
	v_pk_mul_f32 v[58:59], v[54:55], v[58:59]
	v_pk_fma_f32 v[56:57], v[56:57], v[64:65], v[66:67] neg_lo:[0,0,1] neg_hi:[0,0,1]
	v_pk_fma_f32 v[54:55], v[54:55], v[62:63], v[68:69] neg_lo:[0,0,1] neg_hi:[0,0,1]
	v_pk_fma_f32 v[52:53], v[52:53], v[64:65], v[60:61]
	v_pk_fma_f32 v[50:51], v[50:51], v[62:63], v[58:59]
.LBB0_741:
	s_nop 0
	v_cvt_pk_bf16_f32 v50, v50, v51
	v_cvt_pk_bf16_f32 v51, v52, v53
	v_mov_b64_e32 v[52:53], s[36:37]
	v_mad_i64_i32 v[24:25], s[60:61], v24, s77, v[52:53]
	v_lshl_add_u64 v[24:25], s[58:59], 1, v[24:25]
	v_cvt_pk_bf16_f32 v54, v54, v55
	v_cvt_pk_bf16_f32 v55, v56, v57
	v_lshl_add_u64 v[24:25], v[142:143], 1, v[24:25]
	s_and_b64 vcc, exec, s[10:11]
	global_store_dwordx2 v[24:25], v[54:55], off
	global_store_dwordx2 v[24:25], v[50:51], off offset:32
	s_cbranch_vccnz .LBB0_743
	v_mov_b32_e32 v50, v220
	v_mov_b32_e32 v51, v221
	v_mov_b32_e32 v52, v222
	v_mov_b32_e32 v53, v223
	v_mov_b32_e32 v54, v224
	v_mov_b32_e32 v55, v225
	v_mov_b32_e32 v56, v226
	v_mov_b32_e32 v57, v227
	v_pk_mul_f32 v[16:17], v[44:45], v[52:53]
	v_pk_mul_f32 v[22:23], v[42:43], v[50:51]
	v_pk_mul_f32 v[52:53], v[48:49], v[52:53]
	v_pk_mul_f32 v[50:51], v[46:47], v[50:51]
	v_pk_fma_f32 v[48:49], v[48:49], v[56:57], v[16:17] neg_lo:[0,0,1] neg_hi:[0,0,1]
	v_pk_fma_f32 v[46:47], v[46:47], v[54:55], v[22:23] neg_lo:[0,0,1] neg_hi:[0,0,1]
	v_pk_fma_f32 v[44:45], v[44:45], v[56:57], v[52:53]
	v_pk_fma_f32 v[42:43], v[42:43], v[54:55], v[50:51]
; #define GAS __attribute__((address_space(1)))
;     __device__ __forceinline__ void operator()(const f32x4 (&acc)[2][2][4][2], const Unit& u, int wr, int wc, int fr, int fq) const {
;     ...
;                     if ((c0 % 96) == 64) {
;                         const f32x4 cs = *(const GAS f32x4*)(cosT + (size_t)row * 16 + 4 * fq), sn = *(const GAS f32x4*)(sinT + (size_t)row * 16 + 4 * fq);
;                         const f32x4 ra = a * cs - b * sn, rb = b * cs + a * sn; a = ra; b = rb;
;                     }
;                     u32x2 w0, w1; w0.x = pk2(a[0], a[1]); w0.y = pk2(a[2], a[3]); w1.x = pk2(b[0], b[1]); w1.y = pk2(b[2], b[3]);
;                     GAS bf16_t* qp = Q + (size_t)row * 768 + c0 + 4 * fq;
;                     *(GAS u32x2*)qp = w0; *(GAS u32x2*)(qp + 16) = w1;
.LBB0_743:
	v_cvt_pk_bf16_f32 v16, v46, v47
	v_cvt_pk_bf16_f32 v17, v48, v49
	v_cvt_pk_bf16_f32 v22, v42, v43
	v_cvt_pk_bf16_f32 v23, v44, v45
	global_store_dwordx2 v[24:25], v[16:17], off offset:256
	global_store_dwordx2 v[24:25], v[22:23], off offset:288
	v_add_u32_e32 v24, 0xa0, v14
	v_ashrrev_i32_e32 v25, 31, v24
	v_lshlrev_b64 v[16:17], 4, v[24:25]
	v_lshlrev_b64 v[22:23], 2, v[16:17]
	s_and_b64 vcc, exec, s[8:9]
	v_lshl_add_u64 v[16:17], v[144:145], 0, v[22:23]
	v_lshl_add_u64 v[22:23], v[146:147], 0, v[22:23]
	s_cbranch_vccnz .LBB0_745
	v_mov_b32_e32 v42, v228
	v_mov_b32_e32 v43, v229
	v_mov_b32_e32 v44, v230
	v_mov_b32_e32 v45, v231
	v_mov_b32_e32 v46, v232
	v_mov_b32_e32 v47, v233
	v_mov_b32_e32 v48, v234
	v_mov_b32_e32 v49, v235
	v_pk_mul_f32 v[50:51], v[36:37], v[44:45]
	v_pk_mul_f32 v[52:53], v[34:35], v[42:43]
	v_pk_mul_f32 v[44:45], v[40:41], v[44:45]
	v_pk_mul_f32 v[42:43], v[38:39], v[42:43]
	v_pk_fma_f32 v[40:41], v[40:41], v[48:49], v[50:51] neg_lo:[0,0,1] neg_hi:[0,0,1]
	v_pk_fma_f32 v[38:39], v[38:39], v[46:47], v[52:53] neg_lo:[0,0,1] neg_hi:[0,0,1]
	v_pk_fma_f32 v[36:37], v[36:37], v[48:49], v[44:45]
	v_pk_fma_f32 v[34:35], v[34:35], v[46:47], v[42:43]
.LBB0_745:
	s_nop 0
	v_cvt_pk_bf16_f32 v34, v34, v35
	v_cvt_pk_bf16_f32 v35, v36, v37
	v_mov_b64_e32 v[36:37], s[36:37]
	v_mad_i64_i32 v[24:25], s[60:61], v24, s77, v[36:37]
	v_lshl_add_u64 v[24:25], s[58:59], 1, v[24:25]
	v_cvt_pk_bf16_f32 v38, v38, v39
	v_cvt_pk_bf16_f32 v39, v40, v41
	v_lshl_add_u64 v[24:25], v[142:143], 1, v[24:25]
	s_and_b64 vcc, exec, s[10:11]
	global_store_dwordx2 v[24:25], v[38:39], off
	global_store_dwordx2 v[24:25], v[34:35], off offset:32
	s_cbranch_vccnz .LBB0_747
	v_mov_b32_e32 v34, v228
	v_mov_b32_e32 v35, v229
	v_mov_b32_e32 v36, v230
	v_mov_b32_e32 v37, v231
	v_mov_b32_e32 v38, v232
	v_mov_b32_e32 v39, v233
	v_mov_b32_e32 v40, v234
	v_mov_b32_e32 v41, v235
	v_pk_mul_f32 v[16:17], v[28:29], v[36:37]
	v_pk_mul_f32 v[22:23], v[26:27], v[34:35]
	v_pk_mul_f32 v[36:37], v[32:33], v[36:37]
	v_pk_mul_f32 v[34:35], v[30:31], v[34:35]
	v_pk_fma_f32 v[32:33], v[32:33], v[40:41], v[16:17] neg_lo:[0,0,1] neg_hi:[0,0,1]
	v_pk_fma_f32 v[30:31], v[30:31], v[38:39], v[22:23] neg_lo:[0,0,1] neg_hi:[0,0,1]
	v_pk_fma_f32 v[28:29], v[28:29], v[40:41], v[36:37]
	v_pk_fma_f32 v[26:27], v[26:27], v[38:39], v[34:35]
.LBB0_747:
	v_cvt_pk_bf16_f32 v16, v30, v31
	v_cvt_pk_bf16_f32 v17, v32, v33
	v_cvt_pk_bf16_f32 v22, v26, v27
	v_cvt_pk_bf16_f32 v23, v28, v29
	global_store_dwordx2 v[24:25], v[16:17], off offset:256
	global_store_dwordx2 v[24:25], v[22:23], off offset:288
	v_add_u32_e32 v22, 0xb0, v14
	v_ashrrev_i32_e32 v23, 31, v22
	v_lshlrev_b64 v[14:15], 4, v[22:23]
	v_lshlrev_b64 v[16:17], 2, v[14:15]
	s_and_b64 vcc, exec, s[8:9]
	v_lshl_add_u64 v[14:15], v[144:145], 0, v[16:17]
	v_lshl_add_u64 v[16:17], v[146:147], 0, v[16:17]
	s_cbranch_vccnz .LBB0_749
	v_mov_b32_e32 v24, v180
	v_mov_b32_e32 v25, v181
	v_mov_b32_e32 v26, v182
	v_mov_b32_e32 v27, v183
	v_mov_b32_e32 v28, v236
	v_mov_b32_e32 v29, v237
	v_mov_b32_e32 v30, v238
	v_mov_b32_e32 v31, v239
	v_pk_mul_f32 v[32:33], v[12:13], v[26:27]
	v_pk_mul_f32 v[34:35], v[10:11], v[24:25]
	v_pk_mul_f32 v[26:27], v[20:21], v[26:27]
	v_pk_mul_f32 v[24:25], v[18:19], v[24:25]
	v_pk_fma_f32 v[20:21], v[20:21], v[30:31], v[32:33] neg_lo:[0,0,1] neg_hi:[0,0,1]
	v_pk_fma_f32 v[18:19], v[18:19], v[28:29], v[34:35] neg_lo:[0,0,1] neg_hi:[0,0,1]
	v_pk_fma_f32 v[12:13], v[12:13], v[30:31], v[26:27]
	v_pk_fma_f32 v[10:11], v[10:11], v[28:29], v[24:25]
.LBB0_749:
	v_cvt_pk_bf16_f32 v18, v18, v19
	v_cvt_pk_bf16_f32 v19, v20, v21
	v_cvt_pk_bf16_f32 v20, v10, v11
	v_mov_b64_e32 v[10:11], s[36:37]
	v_mad_i64_i32 v[10:11], s[8:9], v22, s77, v[10:11]
	v_lshl_add_u64 v[10:11], s[58:59], 1, v[10:11]
	v_cvt_pk_bf16_f32 v21, v12, v13
	v_lshl_add_u64 v[10:11], v[142:143], 1, v[10:11]
	s_and_b64 vcc, exec, s[10:11]
	global_store_dwordx2 v[10:11], v[18:19], off
	global_store_dwordx2 v[10:11], v[20:21], off offset:32
	s_cbranch_vccnz .LBB0_751
	v_mov_b32_e32 v16, v180
	v_mov_b32_e32 v17, v181
	v_mov_b32_e32 v18, v182
	v_mov_b32_e32 v19, v183
	v_mov_b32_e32 v12, v236
	v_mov_b32_e32 v13, v237
	v_mov_b32_e32 v14, v238
	v_mov_b32_e32 v15, v239
	v_pk_mul_f32 v[20:21], v[4:5], v[18:19]
	v_pk_mul_f32 v[22:23], v[2:3], v[16:17]
	v_pk_mul_f32 v[18:19], v[8:9], v[18:19]
	v_pk_mul_f32 v[16:17], v[6:7], v[16:17]
	v_pk_fma_f32 v[8:9], v[8:9], v[14:15], v[20:21] neg_lo:[0,0,1] neg_hi:[0,0,1]
	v_pk_fma_f32 v[6:7], v[6:7], v[12:13], v[22:23] neg_lo:[0,0,1] neg_hi:[0,0,1]
	v_pk_fma_f32 v[4:5], v[4:5], v[14:15], v[18:19]
	v_pk_fma_f32 v[2:3], v[2:3], v[12:13], v[16:17]
